# QKV GEMM (phase 2) K-loop converted to the same structure: fragment double-buffer, mid-iteration barrier, LDS-DMA operand loads
# speedup vs baseline: 1.0153x; 1.0066x over previous
.LBB0_137:
	v_lshlrev_b32_e32 v4, 4, v2
	v_lshrrev_b32_e32 v1, 3, v2
	v_and_b32_e32 v130, 0x70, v4
	v_mov_b32_e32 v131, 0
	v_lshl_add_u64 v[132:133], s[86:87], 0, v[130:131]
	s_mov_b64 s[0:1], 0x4450000
	v_mul_u32_u24_e32 v4, 0x48, v1
	v_lshl_add_u64 v[134:135], v[132:133], 0, s[0:1]
	v_lshlrev_b32_e32 v4, 1, v4
	s_add_i32 s0, 0, 0x12000
	v_add3_u32 v137, 0, v4, v130
	v_add3_u32 v145, s0, v4, v130
	v_and_b32_e32 v4, 15, v2
	v_lshrrev_b32_e32 v5, 1, v2
	s_movk_i32 s1, 0x180
	v_and_or_b32 v4, v5, s1, v4
	v_mul_u32_u24_e32 v4, 0x90, v4
	v_and_b32_e32 v5, 48, v2
	v_mov_b32_e32 v3, v2
	v_add3_u32 v172, 0, v4, v5
	v_and_b32_e32 v4, 0xcf, v2
	v_mul_u32_u24_e32 v4, 0x90, v4
	v_add3_u32 v173, s0, v4, v5
	v_lshrrev_b32_e32 v4, 1, v1
	v_and_b32_e32 v4, 7, v4
	v_and_b32_e32 v5, 7, v2
	v_xor_b32_e32 v4, v4, v5
	v_lshlrev_b32_e32 v4, 4, v4
	v_lshl_add_u32 v137, v1, 7, v4
	v_add_u32_e32 v145, 0x10000, v137
	v_and_b32_e32 v4, 15, v2
	v_lshrrev_b32_e32 v5, 1, v4
	v_bfe_u32 v216, v2, 4, 2
	v_xor_b32_e32 v5, v5, v216
	v_lshlrev_b32_e32 v5, 4, v5
	v_lshrrev_b32_e32 v216, 8, v2
	v_lshl_add_u32 v216, v216, 7, v4
	v_lshl_add_u32 v172, v216, 7, v5
	v_xor_b32_e32 v216, 64, v172
	v_bfe_u32 v217, v2, 6, 2
	v_lshl_add_u32 v217, v217, 6, v4
	v_lshl_add_u32 v173, v217, 7, v5
	v_add_u32_e32 v173, 0x10000, v173
	v_xor_b32_e32 v217, 64, v173
	v_ashrrev_i32_e32 v4, 1, v3
	v_and_b32_e32 v175, 0xc0, v3
	v_and_b32_e32 v176, 15, v3
	v_bfe_u32 v3, v3, 4, 2
	s_lshr_b32 s3, s2, 3
	s_waitcnt lgkmcnt(0)
	s_and_b32 s17, s2, 7
	v_lshlrev_b32_e32 v130, 4, v3
	v_and_b32_e32 v174, 0xffffff80, v4
	s_add_u32 s10, s86, 0x14c50000
	v_lshl_add_u64 v[4:5], s[86:87], 0, v[130:131]
	s_mov_b64 s[0:1], 0x2fec000
	s_addc_u32 s11, s87, 0
	v_lshl_add_u64 v[138:139], v[4:5], 0, s[0:1]
	s_mov_b64 s[0:1], 0x2fee000
	v_lshlrev_b32_e32 v130, 3, v3
	v_and_b32_e32 v2, 7, v2
	v_lshl_add_u64 v[140:141], v[4:5], 0, s[0:1]
	v_lshl_add_u64 v[4:5], s[86:87], 0, v[130:131]
	s_mov_b64 s[0:1], 0xc850000
	s_add_u32 s12, s86, 0x16d50000
	v_lshlrev_b32_e32 v130, 4, v2
	s_movk_i32 s14, 0xf800
	v_mbcnt_lo_u32_b32 v2, -1, 0
	s_mul_i32 s17, s17, 33
	v_lshlrev_b32_e32 v136, 2, v3
	v_lshl_add_u64 v[142:143], v[4:5], 0, s[0:1]
	s_addc_u32 s13, s87, 0
	v_mul_u32_u24_e32 v144, 0x8400, v3
	s_ashr_i32 s42, s33, 3
	v_lshl_add_u64 v[146:147], s[86:87], 0, v[130:131]
	s_mov_b32 s43, 0x20000
	s_mov_b32 s44, 0x40000
	s_mov_b32 s45, 0x60000
	s_mov_b32 s46, 0x4450000
	s_mov_b32 s47, 0x4470000
	s_mov_b32 s52, 0x4490000
	s_mov_b32 s53, 0x44b0000
	s_movk_i32 s56, 0x500
	s_movk_i32 s57, 0x400
	s_movk_i32 s58, 0x3ff
	v_mov_b32_e32 v177, 0x358637bd
	s_mov_b32 s59, 0x800000
	s_mov_b32 s62, 0x3e0f83e1
	s_movk_i32 s63, 0xff
	s_mov_b32 s15, -1
	s_mov_b32 s16, 0x3e38aa3b
	s_movk_i32 s64, 0xdf00
	s_mov_b32 s65, 0x108000
	s_movk_i32 s66, 0x4000
	s_mov_b32 s67, 0x8000
	s_mov_b32 s68, 0xc000
	s_mov_b32 s69, 0x42000
	s_mov_b32 s70, 0x46000
	s_mov_b32 s71, 0x4a000
	s_mov_b32 s72, 0x4e000
	s_mov_b32 s73, 0x84000
	s_mov_b32 s74, 0x88000
	s_mov_b32 s75, 0x8c000
	s_mov_b32 s80, 0x90000
	s_mov_b32 s81, 0xc6000
	s_mov_b32 s88, 0xca000
	s_mov_b32 s89, 0xce000
	s_mov_b32 s90, 0xd2000
	v_mbcnt_hi_u32_b32 v178, -1, v2
	s_branch .LBB0_140

.LBB0_143:
	s_lshl_b32 s4, s92, 8
	v_or_b32_e32 v2, s4, v1
	s_lshl_b32 s5, s91, 8
	v_ashrrev_i32_e32 v3, 31, v2
	v_or_b32_e32 v4, s5, v1
	v_lshlrev_b64 v[62:63], 11, v[2:3]
	v_ashrrev_i32_e32 v5, 31, v4
	v_lshl_add_u64 v[2:3], v[134:135], 0, v[62:63]
	v_lshlrev_b64 v[4:5], 11, v[4:5]
	v_lshl_add_u64 v[148:149], v[132:133], 0, v[4:5]
	v_add_co_u32_e32 v4, vcc, 0x20000, v2
	s_mov_b32 s6, 0
	s_nop 0
	v_addc_co_u32_e32 v5, vcc, 0, v3, vcc
	global_load_dwordx4 v[30:33], v[2:3], off
	global_load_dwordx4 v[34:37], v[4:5], off
	v_add_co_u32_e32 v4, vcc, 0x40000, v2
	s_mov_b64 s[0:1], 0
	s_nop 0
	v_addc_co_u32_e32 v5, vcc, 0, v3, vcc
	v_add_co_u32_e32 v2, vcc, 0x60000, v2
	v_lshl_add_u64 v[150:151], v[146:147], 0, v[62:63]
	s_nop 0
	v_addc_co_u32_e32 v3, vcc, 0, v3, vcc
	global_load_dwordx4 v[38:41], v[4:5], off
	global_load_dwordx4 v[42:45], v[2:3], off
	v_add_co_u32_e32 v2, vcc, s43, v148
	s_nop 1
	v_addc_co_u32_e32 v3, vcc, 0, v149, vcc
	s_barrier
	global_load_dwordx4 v[46:49], v[148:149], off
	global_load_dwordx4 v[50:53], v[2:3], off
	v_add_co_u32_e32 v2, vcc, s44, v148
	s_nop 1
	v_addc_co_u32_e32 v3, vcc, 0, v149, vcc
	v_add_co_u32_e32 v4, vcc, 0x60000, v148
	s_nop 1
	v_addc_co_u32_e32 v5, vcc, 0, v149, vcc
	global_load_dwordx4 v[54:57], v[2:3], off
	global_load_dwordx4 v[58:61], v[4:5], off
	v_mov_b32_e32 v2, 0
	v_mov_b32_e32 v3, v2
	v_mov_b32_e32 v4, v2
	v_mov_b32_e32 v5, v2
	v_mov_b32_e32 v6, v2
	v_mov_b32_e32 v7, v2
	v_mov_b32_e32 v8, v2
	v_mov_b32_e32 v9, v2
	v_mov_b32_e32 v10, v2
	v_mov_b32_e32 v11, v2
	v_mov_b32_e32 v12, v2
	v_mov_b32_e32 v13, v2
	v_mov_b32_e32 v14, v2
	v_mov_b32_e32 v15, v2
	v_mov_b32_e32 v16, v2
	v_mov_b32_e32 v17, v2
	v_mov_b32_e32 v18, v2
	v_mov_b32_e32 v19, v2
	v_mov_b32_e32 v20, v2
	v_mov_b32_e32 v21, v2
	v_mov_b32_e32 v22, v2
	v_mov_b32_e32 v23, v2
	v_mov_b32_e32 v24, v2
	v_mov_b32_e32 v25, v2
	v_mov_b32_e32 v26, v2
	v_mov_b32_e32 v27, v2
	v_mov_b32_e32 v28, v2
	v_mov_b32_e32 v29, v2
	v_mov_b32_e32 v62, v2
	v_mov_b32_e32 v63, v2
	v_mov_b32_e32 v64, v2
	v_mov_b32_e32 v65, v2
	v_mov_b32_e32 v66, v2
	v_mov_b32_e32 v67, v2
	v_mov_b32_e32 v68, v2
	v_mov_b32_e32 v69, v2
	v_mov_b32_e32 v70, v2
	v_mov_b32_e32 v71, v2
	v_mov_b32_e32 v72, v2
	v_mov_b32_e32 v73, v2
	v_mov_b32_e32 v74, v2
	v_mov_b32_e32 v75, v2
	v_mov_b32_e32 v76, v2
	v_mov_b32_e32 v77, v2
	v_mov_b32_e32 v78, v2
	v_mov_b32_e32 v79, v2
	v_mov_b32_e32 v80, v2
	v_mov_b32_e32 v81, v2
	v_mov_b32_e32 v82, v2
	v_mov_b32_e32 v83, v2
	s_waitcnt vmcnt(7)
	ds_write_b128 v137, v[30:33]
	s_waitcnt vmcnt(6)
	ds_write_b128 v137, v[34:37] offset:8192
	s_waitcnt vmcnt(5)
	ds_write_b128 v137, v[38:41] offset:16384
	s_waitcnt vmcnt(4)
	ds_write_b128 v137, v[42:45] offset:24576
	s_waitcnt vmcnt(3)
	ds_write_b128 v145, v[46:49]
	s_waitcnt vmcnt(2)
	ds_write_b128 v145, v[50:53] offset:8192
	s_waitcnt vmcnt(1)
	ds_write_b128 v145, v[54:57] offset:16384
	s_waitcnt vmcnt(0)
	ds_write_b128 v145, v[58:61] offset:24576
	v_mov_b32_e32 v30, v2
	v_mov_b32_e32 v31, v2
	v_mov_b32_e32 v32, v2
	v_mov_b32_e32 v33, v2
	v_mov_b32_e32 v34, v2
	v_mov_b32_e32 v35, v2
	v_mov_b32_e32 v36, v2
	v_mov_b32_e32 v37, v2
	v_mov_b32_e32 v38, v2
	v_mov_b32_e32 v39, v2
	v_mov_b32_e32 v40, v2
	v_mov_b32_e32 v41, v2
	v_mov_b32_e32 v42, v2
	v_mov_b32_e32 v43, v2
	v_mov_b32_e32 v44, v2
	v_mov_b32_e32 v45, v2
	v_mov_b32_e32 v46, v2
	v_mov_b32_e32 v47, v2
	v_mov_b32_e32 v48, v2
	v_mov_b32_e32 v49, v2
	v_mov_b32_e32 v50, v2
	v_mov_b32_e32 v51, v2
	v_mov_b32_e32 v52, v2
	v_mov_b32_e32 v53, v2
	v_mov_b32_e32 v54, v2
	v_mov_b32_e32 v55, v2
	v_mov_b32_e32 v56, v2
	v_mov_b32_e32 v57, v2
	v_mov_b32_e32 v58, v2
	v_mov_b32_e32 v59, v2
	v_mov_b32_e32 v60, v2
	v_mov_b32_e32 v61, v2
	v_mov_b32_e32 v84, v2
	v_mov_b32_e32 v85, v2
	v_mov_b32_e32 v86, v2
	v_mov_b32_e32 v87, v2
	v_mov_b32_e32 v88, v2
	v_mov_b32_e32 v89, v2
	v_mov_b32_e32 v90, v2
	v_mov_b32_e32 v91, v2
	v_mov_b32_e32 v92, v2
	v_mov_b32_e32 v93, v2
	v_mov_b32_e32 v94, v2
	v_mov_b32_e32 v95, v2
	v_mov_b32_e32 v96, v2
	v_mov_b32_e32 v97, v2
	v_mov_b32_e32 v98, v2
	v_mov_b32_e32 v99, v2
	v_mov_b32_e32 v100, v2
	v_mov_b32_e32 v101, v2
	v_mov_b32_e32 v102, v2
	v_mov_b32_e32 v103, v2
	v_mov_b32_e32 v104, v2
	v_mov_b32_e32 v105, v2
	v_mov_b32_e32 v106, v2
	v_mov_b32_e32 v107, v2
	v_mov_b32_e32 v108, v2
	v_mov_b32_e32 v109, v2
	v_mov_b32_e32 v110, v2
	v_mov_b32_e32 v111, v2
	v_mov_b32_e32 v112, v2
	v_mov_b32_e32 v113, v2
	v_mov_b32_e32 v114, v2
	v_mov_b32_e32 v115, v2
	v_mov_b32_e32 v116, v2
	v_mov_b32_e32 v117, v2
	v_mov_b32_e32 v118, v2
	v_mov_b32_e32 v119, v2
	v_mov_b32_e32 v120, v2
	v_mov_b32_e32 v121, v2
	v_mov_b32_e32 v122, v2
	v_mov_b32_e32 v123, v2
	v_mov_b32_e32 v124, v2
	v_mov_b32_e32 v125, v2
	v_mov_b32_e32 v126, v2
	v_mov_b32_e32 v127, v2
	v_mov_b32_e32 v128, v2
	v_mov_b32_e32 v129, v2
	s_waitcnt lgkmcnt(0)
	s_barrier
	s_movk_i32 s97, 0x70
	v_readfirstlane_b32 s98, v150
	v_readfirstlane_b32 s99, v151
	v_subrev_u32_e32 v157, s98, v150
	v_bfi_b32 v157, s97, v137, v157
	v_add_u32_e32 v160, s46, v157
	v_add_u32_e32 v161, s47, v157
	v_add_u32_e32 v162, s52, v157
	v_add_u32_e32 v163, s53, v157
	s_add_u32 s98, s98, s0
	s_addc_u32 s99, s99, s1
	s_add_u32 s98, s98, 0x80
	s_addc_u32 s99, s99, 0
	v_readfirstlane_b32 s100, v148
	v_readfirstlane_b32 s101, v149
	v_subrev_u32_e32 v159, s100, v148
	v_bfi_b32 v159, s97, v137, v159
	v_add_u32_e32 v164, 0, v159
	v_add_u32_e32 v165, s43, v159
	v_add_u32_e32 v166, s44, v159
	v_add_u32_e32 v167, s45, v159
	s_add_u32 s100, s100, s0
	s_addc_u32 s101, s101, s1
	s_add_u32 s100, s100, 0x80
	s_addc_u32 s101, s101, 0
	v_readfirstlane_b32 s96, v137
	s_and_b32 s96, s96, 0xfc00
	s_xor_b32 s96, s96, 0x8000
	s_mov_b32 m0, s96
	s_nop 0
	global_load_lds_dwordx4 v160, s[98:99]
	s_add_u32 m0, m0, 0x2000
	s_nop 0
	global_load_lds_dwordx4 v161, s[98:99]
	s_add_u32 m0, m0, 0x2000
	s_nop 0
	global_load_lds_dwordx4 v162, s[98:99]
	s_add_u32 m0, m0, 0x2000
	s_nop 0
	global_load_lds_dwordx4 v163, s[98:99]
	s_add_u32 m0, m0, 0xa000
	s_nop 0
	global_load_lds_dwordx4 v164, s[100:101]
	s_add_u32 m0, m0, 0x2000
	s_nop 0
	global_load_lds_dwordx4 v165, s[100:101]
	s_add_u32 m0, m0, 0x2000
	s_nop 0
	global_load_lds_dwordx4 v166, s[100:101]
	s_add_u32 m0, m0, 0x2000
	s_nop 0
	global_load_lds_dwordx4 v167, s[100:101]
	v_mov_b32_e32 v156, v172
	v_mov_b32_e32 v158, v173
	ds_read_b128 v[192:195], v156
	ds_read_b128 v[196:199], v156 offset:2048
	ds_read_b128 v[200:203], v156 offset:4096
	ds_read_b128 v[204:207], v156 offset:6144
	ds_read_b128 v[228:231], v158
	ds_read_b128 v[232:235], v158 offset:2048
	ds_read_b128 v[236:239], v158 offset:4096
	ds_read_b128 v[240:243], v158 offset:6144
.Lg2_p2_loop:
	ds_read_b128 v[208:211], v156 offset:8192
	ds_read_b128 v[212:215], v156 offset:10240
	ds_read_b128 v[218:221], v156 offset:12288
	ds_read_b128 v[224:227], v156 offset:14336
	s_waitcnt lgkmcnt(4)
	v_mfma_f32_16x16x32_bf16 v[126:129], v[228:231], v[192:195], v[126:129]
	v_mfma_f32_16x16x32_bf16 v[122:125], v[232:235], v[192:195], v[122:125]
	v_mfma_f32_16x16x32_bf16 v[118:121], v[236:239], v[192:195], v[118:121]
	v_mfma_f32_16x16x32_bf16 v[114:117], v[240:243], v[192:195], v[114:117]
	v_mfma_f32_16x16x32_bf16 v[110:113], v[228:231], v[196:199], v[110:113]
	v_mfma_f32_16x16x32_bf16 v[106:109], v[232:235], v[196:199], v[106:109]
	v_mfma_f32_16x16x32_bf16 v[102:105], v[236:239], v[196:199], v[102:105]
	v_mfma_f32_16x16x32_bf16 v[98:101], v[240:243], v[196:199], v[98:101]
	v_mfma_f32_16x16x32_bf16 v[94:97], v[228:231], v[200:203], v[94:97]
	v_mfma_f32_16x16x32_bf16 v[90:93], v[232:235], v[200:203], v[90:93]
	v_mfma_f32_16x16x32_bf16 v[86:89], v[236:239], v[200:203], v[86:89]
	v_mfma_f32_16x16x32_bf16 v[82:85], v[240:243], v[200:203], v[82:85]
	v_mfma_f32_16x16x32_bf16 v[78:81], v[228:231], v[204:207], v[78:81]
	v_mfma_f32_16x16x32_bf16 v[74:77], v[232:235], v[204:207], v[74:77]
	v_mfma_f32_16x16x32_bf16 v[70:73], v[236:239], v[204:207], v[70:73]
	v_mfma_f32_16x16x32_bf16 v[66:69], v[240:243], v[204:207], v[66:69]
	ds_read_b128 v[192:195], v216
	ds_read_b128 v[196:199], v216 offset:2048
	ds_read_b128 v[200:203], v216 offset:4096
	ds_read_b128 v[204:207], v216 offset:6144
	ds_read_b128 v[244:247], v217
	ds_read_b128 v[248:251], v217 offset:2048
	ds_read_b128 v[252:255], v217 offset:4096
	ds_read_b128 v[152:155], v217 offset:6144
	s_waitcnt lgkmcnt(8)
	v_mfma_f32_16x16x32_bf16 v[62:65], v[228:231], v[208:211], v[62:65]
	v_mfma_f32_16x16x32_bf16 v[58:61], v[232:235], v[208:211], v[58:61]
	v_mfma_f32_16x16x32_bf16 v[54:57], v[236:239], v[208:211], v[54:57]
	v_mfma_f32_16x16x32_bf16 v[50:53], v[240:243], v[208:211], v[50:53]
	v_mfma_f32_16x16x32_bf16 v[46:49], v[228:231], v[212:215], v[46:49]
	v_mfma_f32_16x16x32_bf16 v[42:45], v[232:235], v[212:215], v[42:45]
	v_mfma_f32_16x16x32_bf16 v[38:41], v[236:239], v[212:215], v[38:41]
	v_mfma_f32_16x16x32_bf16 v[34:37], v[240:243], v[212:215], v[34:37]
	v_mfma_f32_16x16x32_bf16 v[30:33], v[228:231], v[218:221], v[30:33]
	v_mfma_f32_16x16x32_bf16 v[26:29], v[232:235], v[218:221], v[26:29]
	v_mfma_f32_16x16x32_bf16 v[22:25], v[236:239], v[218:221], v[22:25]
	v_mfma_f32_16x16x32_bf16 v[18:21], v[240:243], v[218:221], v[18:21]
	v_mfma_f32_16x16x32_bf16 v[14:17], v[228:231], v[224:227], v[14:17]
	v_mfma_f32_16x16x32_bf16 v[10:13], v[232:235], v[224:227], v[10:13]
	v_mfma_f32_16x16x32_bf16 v[6:9], v[236:239], v[224:227], v[6:9]
	v_mfma_f32_16x16x32_bf16 v[2:5], v[240:243], v[224:227], v[2:5]
	ds_read_b128 v[208:211], v216 offset:8192
	ds_read_b128 v[212:215], v216 offset:10240
	ds_read_b128 v[218:221], v216 offset:12288
	ds_read_b128 v[224:227], v216 offset:14336
	s_waitcnt lgkmcnt(4)
	v_mfma_f32_16x16x32_bf16 v[126:129], v[244:247], v[192:195], v[126:129]
	v_mfma_f32_16x16x32_bf16 v[122:125], v[248:251], v[192:195], v[122:125]
	v_mfma_f32_16x16x32_bf16 v[118:121], v[252:255], v[192:195], v[118:121]
	v_mfma_f32_16x16x32_bf16 v[114:117], v[152:155], v[192:195], v[114:117]
	v_mfma_f32_16x16x32_bf16 v[110:113], v[244:247], v[196:199], v[110:113]
	v_mfma_f32_16x16x32_bf16 v[106:109], v[248:251], v[196:199], v[106:109]
	v_mfma_f32_16x16x32_bf16 v[102:105], v[252:255], v[196:199], v[102:105]
	v_mfma_f32_16x16x32_bf16 v[98:101], v[152:155], v[196:199], v[98:101]
	v_mfma_f32_16x16x32_bf16 v[94:97], v[244:247], v[200:203], v[94:97]
	v_mfma_f32_16x16x32_bf16 v[90:93], v[248:251], v[200:203], v[90:93]
	v_mfma_f32_16x16x32_bf16 v[86:89], v[252:255], v[200:203], v[86:89]
	v_mfma_f32_16x16x32_bf16 v[82:85], v[152:155], v[200:203], v[82:85]
	v_mfma_f32_16x16x32_bf16 v[78:81], v[244:247], v[204:207], v[78:81]
	v_mfma_f32_16x16x32_bf16 v[74:77], v[248:251], v[204:207], v[74:77]
	v_mfma_f32_16x16x32_bf16 v[70:73], v[252:255], v[204:207], v[70:73]
	v_mfma_f32_16x16x32_bf16 v[66:69], v[152:155], v[204:207], v[66:69]
	s_waitcnt vmcnt(0)
	s_waitcnt lgkmcnt(0)
	s_barrier
	s_add_u32 s0, s0, 0x80
	s_addc_u32 s1, s1, 0
	s_add_u32 s98, s98, 0x80
	s_addc_u32 s99, s99, 0
	s_add_u32 s100, s100, 0x80
	s_addc_u32 s101, s101, 0
	s_cmpk_eq_i32 s0, 0x780
	s_cbranch_scc1 .Lg2_p2_tail
	v_xor_b32_e32 v156, 0x8000, v156
	v_xor_b32_e32 v158, 0x8000, v158
	v_xor_b32_e32 v216, 0x8000, v216
	v_xor_b32_e32 v217, 0x8000, v217
	s_xor_b32 s96, s96, 0x8000
	ds_read_b128 v[192:195], v156
	ds_read_b128 v[196:199], v156 offset:2048
	ds_read_b128 v[200:203], v156 offset:4096
	ds_read_b128 v[204:207], v156 offset:6144
	ds_read_b128 v[228:231], v158
	ds_read_b128 v[232:235], v158 offset:2048
	ds_read_b128 v[236:239], v158 offset:4096
	ds_read_b128 v[240:243], v158 offset:6144
	v_mfma_f32_16x16x32_bf16 v[62:65], v[244:247], v[208:211], v[62:65]
	s_mov_b32 m0, s96
	v_mfma_f32_16x16x32_bf16 v[58:61], v[248:251], v[208:211], v[58:61]
	global_load_lds_dwordx4 v160, s[98:99]
	v_mfma_f32_16x16x32_bf16 v[54:57], v[252:255], v[208:211], v[54:57]
	s_add_u32 m0, m0, 0x2000
	v_mfma_f32_16x16x32_bf16 v[50:53], v[152:155], v[208:211], v[50:53]
	global_load_lds_dwordx4 v161, s[98:99]
	v_mfma_f32_16x16x32_bf16 v[46:49], v[244:247], v[212:215], v[46:49]
	s_add_u32 m0, m0, 0x2000
	v_mfma_f32_16x16x32_bf16 v[42:45], v[248:251], v[212:215], v[42:45]
	global_load_lds_dwordx4 v162, s[98:99]
	v_mfma_f32_16x16x32_bf16 v[38:41], v[252:255], v[212:215], v[38:41]
	s_add_u32 m0, m0, 0x2000
	v_mfma_f32_16x16x32_bf16 v[34:37], v[152:155], v[212:215], v[34:37]
	global_load_lds_dwordx4 v163, s[98:99]
	v_mfma_f32_16x16x32_bf16 v[30:33], v[244:247], v[218:221], v[30:33]
	s_add_u32 m0, m0, 0xa000
	v_mfma_f32_16x16x32_bf16 v[26:29], v[248:251], v[218:221], v[26:29]
	global_load_lds_dwordx4 v164, s[100:101]
	v_mfma_f32_16x16x32_bf16 v[22:25], v[252:255], v[218:221], v[22:25]
	s_add_u32 m0, m0, 0x2000
	v_mfma_f32_16x16x32_bf16 v[18:21], v[152:155], v[218:221], v[18:21]
	global_load_lds_dwordx4 v165, s[100:101]
	v_mfma_f32_16x16x32_bf16 v[14:17], v[244:247], v[224:227], v[14:17]
	s_add_u32 m0, m0, 0x2000
	v_mfma_f32_16x16x32_bf16 v[10:13], v[248:251], v[224:227], v[10:13]
	global_load_lds_dwordx4 v166, s[100:101]
	v_mfma_f32_16x16x32_bf16 v[6:9], v[252:255], v[224:227], v[6:9]
	s_add_u32 m0, m0, 0x2000
	v_mfma_f32_16x16x32_bf16 v[2:5], v[152:155], v[224:227], v[2:5]
	global_load_lds_dwordx4 v167, s[100:101]
	s_branch .Lg2_p2_loop
.Lg2_p2_tail:
	v_xor_b32_e32 v216, 64, v172
	v_xor_b32_e32 v217, 64, v173
	v_mfma_f32_16x16x32_bf16 v[62:65], v[244:247], v[208:211], v[62:65]
	v_mfma_f32_16x16x32_bf16 v[58:61], v[248:251], v[208:211], v[58:61]
	v_mfma_f32_16x16x32_bf16 v[54:57], v[252:255], v[208:211], v[54:57]
	v_mfma_f32_16x16x32_bf16 v[50:53], v[152:155], v[208:211], v[50:53]
	v_mfma_f32_16x16x32_bf16 v[46:49], v[244:247], v[212:215], v[46:49]
	v_mfma_f32_16x16x32_bf16 v[42:45], v[248:251], v[212:215], v[42:45]
	v_mfma_f32_16x16x32_bf16 v[38:41], v[252:255], v[212:215], v[38:41]
	v_mfma_f32_16x16x32_bf16 v[34:37], v[152:155], v[212:215], v[34:37]
	v_mfma_f32_16x16x32_bf16 v[30:33], v[244:247], v[218:221], v[30:33]
	v_mfma_f32_16x16x32_bf16 v[26:29], v[248:251], v[218:221], v[26:29]
	v_mfma_f32_16x16x32_bf16 v[22:25], v[252:255], v[218:221], v[22:25]
	v_mfma_f32_16x16x32_bf16 v[18:21], v[152:155], v[218:221], v[18:21]
	v_mfma_f32_16x16x32_bf16 v[14:17], v[244:247], v[224:227], v[14:17]
	v_mfma_f32_16x16x32_bf16 v[10:13], v[248:251], v[224:227], v[10:13]
	v_mfma_f32_16x16x32_bf16 v[6:9], v[252:255], v[224:227], v[6:9]
	v_mfma_f32_16x16x32_bf16 v[2:5], v[152:155], v[224:227], v[2:5]
	ds_read_b128 v[148:151], v173 offset:32768
	ds_read_b128 v[152:155], v173 offset:34816
	ds_read_b128 v[156:159], v173 offset:36864
	ds_read_b128 v[160:163], v173 offset:38912
	ds_read_b128 v[164:167], v172 offset:32768
	ds_read_b128 v[168:171], v172 offset:34816
	ds_read_b128 v[180:183], v172 offset:36864
	ds_read_b128 v[184:187], v172 offset:38912
	s_setprio 1
	s_waitcnt lgkmcnt(3)
	v_mfma_f32_16x16x32_bf16 v[126:129], v[148:151], v[164:167], v[126:129]
	v_mfma_f32_16x16x32_bf16 v[122:125], v[152:155], v[164:167], v[122:125]
	v_mfma_f32_16x16x32_bf16 v[118:121], v[156:159], v[164:167], v[118:121]
	v_mfma_f32_16x16x32_bf16 v[114:117], v[160:163], v[164:167], v[114:117]
	s_waitcnt lgkmcnt(2)
	v_mfma_f32_16x16x32_bf16 v[110:113], v[148:151], v[168:171], v[110:113]
	v_mfma_f32_16x16x32_bf16 v[106:109], v[152:155], v[168:171], v[106:109]
	v_mfma_f32_16x16x32_bf16 v[102:105], v[156:159], v[168:171], v[102:105]
	v_mfma_f32_16x16x32_bf16 v[98:101], v[160:163], v[168:171], v[98:101]
	s_waitcnt lgkmcnt(1)
	v_mfma_f32_16x16x32_bf16 v[94:97], v[148:151], v[180:183], v[94:97]
	v_mfma_f32_16x16x32_bf16 v[90:93], v[152:155], v[180:183], v[90:93]
	v_mfma_f32_16x16x32_bf16 v[86:89], v[156:159], v[180:183], v[86:89]
	v_mfma_f32_16x16x32_bf16 v[82:85], v[160:163], v[180:183], v[82:85]
	s_waitcnt lgkmcnt(0)
	v_mfma_f32_16x16x32_bf16 v[78:81], v[148:151], v[184:187], v[78:81]
	v_mfma_f32_16x16x32_bf16 v[74:77], v[152:155], v[184:187], v[74:77]
	v_mfma_f32_16x16x32_bf16 v[70:73], v[156:159], v[184:187], v[70:73]
	v_mfma_f32_16x16x32_bf16 v[66:69], v[160:163], v[184:187], v[66:69]
	s_setprio 0
	ds_read_b128 v[164:167], v172 offset:40960
	ds_read_b128 v[168:171], v172 offset:43008
	ds_read_b128 v[180:183], v172 offset:45056
	ds_read_b128 v[184:187], v172 offset:47104
	s_setprio 1
	s_waitcnt lgkmcnt(3)
	v_mfma_f32_16x16x32_bf16 v[62:65], v[148:151], v[164:167], v[62:65]
	v_mfma_f32_16x16x32_bf16 v[58:61], v[152:155], v[164:167], v[58:61]
	v_mfma_f32_16x16x32_bf16 v[54:57], v[156:159], v[164:167], v[54:57]
	v_mfma_f32_16x16x32_bf16 v[50:53], v[160:163], v[164:167], v[50:53]
	s_waitcnt lgkmcnt(2)
	v_mfma_f32_16x16x32_bf16 v[46:49], v[148:151], v[168:171], v[46:49]
	v_mfma_f32_16x16x32_bf16 v[42:45], v[152:155], v[168:171], v[42:45]
	v_mfma_f32_16x16x32_bf16 v[38:41], v[156:159], v[168:171], v[38:41]
	v_mfma_f32_16x16x32_bf16 v[34:37], v[160:163], v[168:171], v[34:37]
	s_waitcnt lgkmcnt(1)
	v_mfma_f32_16x16x32_bf16 v[30:33], v[148:151], v[180:183], v[30:33]
	v_mfma_f32_16x16x32_bf16 v[26:29], v[152:155], v[180:183], v[26:29]
	v_mfma_f32_16x16x32_bf16 v[22:25], v[156:159], v[180:183], v[22:25]
	v_mfma_f32_16x16x32_bf16 v[18:21], v[160:163], v[180:183], v[18:21]
	s_waitcnt lgkmcnt(0)
	v_mfma_f32_16x16x32_bf16 v[148:151], v[148:151], v[184:187], v[14:17]
	v_mfma_f32_16x16x32_bf16 v[152:155], v[152:155], v[184:187], v[10:13]
	v_mfma_f32_16x16x32_bf16 v[156:159], v[156:159], v[184:187], v[6:9]
	v_mfma_f32_16x16x32_bf16 v[160:163], v[160:163], v[184:187], v[2:5]
	s_setprio 0
	ds_read_b128 v[164:167], v217 offset:32768
	ds_read_b128 v[168:171], v217 offset:34816
	ds_read_b128 v[180:183], v217 offset:36864
	ds_read_b128 v[184:187], v217 offset:38912
	ds_read_b128 v[2:5], v216 offset:32768
	ds_read_b128 v[188:191], v216 offset:34816
	ds_read_b128 v[192:195], v216 offset:36864
	ds_read_b128 v[196:199], v216 offset:38912
	s_setprio 1
	s_waitcnt lgkmcnt(3)
	v_mfma_f32_16x16x32_bf16 v[14:17], v[164:167], v[2:5], v[126:129]
	v_mfma_f32_16x16x32_bf16 v[10:13], v[168:171], v[2:5], v[122:125]
	v_mfma_f32_16x16x32_bf16 v[6:9], v[180:183], v[2:5], v[118:121]
	v_mfma_f32_16x16x32_bf16 v[2:5], v[184:187], v[2:5], v[114:117]
	s_waitcnt lgkmcnt(2)
	v_mfma_f32_16x16x32_bf16 v[126:129], v[164:167], v[188:191], v[110:113]
	v_mfma_f32_16x16x32_bf16 v[122:125], v[168:171], v[188:191], v[106:109]
	v_mfma_f32_16x16x32_bf16 v[118:121], v[180:183], v[188:191], v[102:105]
	v_mfma_f32_16x16x32_bf16 v[114:117], v[184:187], v[188:191], v[98:101]
	s_waitcnt lgkmcnt(1)
	v_mfma_f32_16x16x32_bf16 v[110:113], v[164:167], v[192:195], v[94:97]
	v_mfma_f32_16x16x32_bf16 v[106:109], v[168:171], v[192:195], v[90:93]
	v_mfma_f32_16x16x32_bf16 v[102:105], v[180:183], v[192:195], v[86:89]
	v_mfma_f32_16x16x32_bf16 v[98:101], v[184:187], v[192:195], v[82:85]
	s_waitcnt lgkmcnt(0)
	v_mfma_f32_16x16x32_bf16 v[94:97], v[164:167], v[196:199], v[78:81]
	v_mfma_f32_16x16x32_bf16 v[90:93], v[168:171], v[196:199], v[74:77]
	v_mfma_f32_16x16x32_bf16 v[86:89], v[180:183], v[196:199], v[70:73]
	v_mfma_f32_16x16x32_bf16 v[82:85], v[184:187], v[196:199], v[66:69]
	s_setprio 0
	s_nop 1
	ds_read_b128 v[66:69], v216 offset:40960
	ds_read_b128 v[188:191], v216 offset:43008
	ds_read_b128 v[192:195], v216 offset:45056
	ds_read_b128 v[196:199], v216 offset:47104
	s_setprio 1
	s_waitcnt lgkmcnt(3)
	v_mfma_f32_16x16x32_bf16 v[78:81], v[164:167], v[66:69], v[62:65]
	v_mfma_f32_16x16x32_bf16 v[74:77], v[168:171], v[66:69], v[58:61]
	v_mfma_f32_16x16x32_bf16 v[70:73], v[180:183], v[66:69], v[54:57]
	v_mfma_f32_16x16x32_bf16 v[66:69], v[184:187], v[66:69], v[50:53]
	s_waitcnt lgkmcnt(2)
	v_mfma_f32_16x16x32_bf16 v[62:65], v[164:167], v[188:191], v[46:49]
	v_mfma_f32_16x16x32_bf16 v[58:61], v[168:171], v[188:191], v[42:45]
	v_mfma_f32_16x16x32_bf16 v[54:57], v[180:183], v[188:191], v[38:41]
	v_mfma_f32_16x16x32_bf16 v[50:53], v[184:187], v[188:191], v[34:37]
	s_waitcnt lgkmcnt(1)
	v_mfma_f32_16x16x32_bf16 v[46:49], v[164:167], v[192:195], v[30:33]
	v_mfma_f32_16x16x32_bf16 v[42:45], v[168:171], v[192:195], v[26:29]
	v_mfma_f32_16x16x32_bf16 v[38:41], v[180:183], v[192:195], v[22:25]
	v_mfma_f32_16x16x32_bf16 v[34:37], v[184:187], v[192:195], v[18:21]
	s_waitcnt lgkmcnt(0)
	v_mfma_f32_16x16x32_bf16 v[30:33], v[164:167], v[196:199], v[148:151]
	v_mfma_f32_16x16x32_bf16 v[26:29], v[168:171], v[196:199], v[152:155]
	v_mfma_f32_16x16x32_bf16 v[22:25], v[180:183], v[196:199], v[156:159]
	v_mfma_f32_16x16x32_bf16 v[18:21], v[184:187], v[196:199], v[160:163]
	s_setprio 0
	v_add_u32_e32 v179, s4, v174
	v_or_b32_e32 v130, s5, v175
	v_ashrrev_i32_e32 v149, 31, v130
	v_mov_b32_e32 v148, v130
	v_or_b32_e32 v154, v179, v176
	v_cmp_gt_i32_e64 s[4:5], s56, v130
	v_cmp_gt_i32_e64 s[6:7], s57, v130
	v_cmp_lt_i32_e64 s[0:1], s58, v130
	v_lshl_add_u64 v[150:151], v[130:131], 1, s[10:11]
	v_lshl_add_u64 v[148:149], v[148:149], 1, v[142:143]
	v_lshlrev_b32_e32 v152, 2, v136
	v_mul_hi_i32 v155, v154, s62
	s_barrier
	s_and_saveexec_b64 s[28:29], s[4:5]
	s_xor_b64 s[28:29], exec, s[28:29]
	s_cbranch_execz .LBB0_171
	v_mov_b32_e32 v153, s79
	v_mov_b32_e32 v156, s77
	v_cndmask_b32_e64 v157, v153, v156, s[6:7]
	v_mov_b32_e32 v153, s78
	v_mov_b32_e32 v156, s76
	v_cndmask_b32_e64 v156, v153, v156, s[6:7]
	v_mov_b32_e32 v153, v131
	v_lshl_add_u64 v[156:157], v[156:157], 0, v[152:153]
	global_load_dwordx4 v[158:161], v[156:157], off
	global_load_dwordx4 v[164:167], v[156:157], off offset:64
	global_load_dwordx4 v[182:185], v[156:157], off offset:128
	global_load_dwordx4 v[186:189], v[156:157], off offset:192
	v_mul_f32_e32 v191, v15, v15
	v_fmac_f32_e32 v191, v14, v14
	v_fmac_f32_e32 v191, v16, v16
	v_fmac_f32_e32 v191, v17, v17
	v_fmac_f32_e32 v191, v10, v10
	v_fmac_f32_e32 v191, v11, v11
	v_fmac_f32_e32 v191, v12, v12
	v_pk_mul_f32 v[168:169], v[6:7], v[6:7]
	v_fmac_f32_e32 v191, v13, v13
	v_add_f32_e32 v168, v168, v191
	v_pk_mul_f32 v[162:163], v[8:9], v[8:9]
	v_add_f32_e32 v168, v169, v168
	v_add_f32_e32 v162, v162, v168
	v_and_b32_e32 v190, 64, v178
	v_pk_mul_f32 v[180:181], v[2:3], v[2:3]
	v_add_f32_e32 v162, v163, v162
	v_xor_b32_e32 v153, 16, v178
	v_add_u32_e32 v190, 64, v190
	v_add_f32_e32 v162, v180, v162
	v_pk_mul_f32 v[170:171], v[4:5], v[4:5]
	v_cmp_lt_i32_e32 vcc, v153, v190
	v_add_f32_e32 v162, v181, v162
	v_add_f32_e32 v162, v170, v162
	v_cndmask_b32_e32 v153, v178, v153, vcc
	v_lshlrev_b32_e32 v153, 2, v153
	v_add_f32_e32 v162, v171, v162
	ds_bpermute_b32 v163, v153, v162
	v_xor_b32_e32 v168, 32, v178
	v_cmp_lt_i32_e32 vcc, v168, v190
	s_waitcnt lgkmcnt(0)
	v_add_f32_e32 v162, v162, v163
	v_cndmask_b32_e32 v168, v178, v168, vcc
	v_lshlrev_b32_e32 v180, 2, v168
	ds_bpermute_b32 v163, v180, v162
	v_lshrrev_b32_e32 v168, 31, v155
	v_ashrrev_i32_e32 v155, 11, v155
	v_add_u32_e32 v155, v155, v168
	v_mul_i32_i24_e32 v155, 0x2100, v155
	s_waitcnt lgkmcnt(0)
	v_add_f32_e32 v162, v162, v163
	v_fmamk_f32 v162, v162, 0x3c800000, v177
	v_mul_f32_e32 v163, 0x4b800000, v162
	v_cmp_gt_f32_e32 vcc, s59, v162
	v_sub_u32_e32 v155, v154, v155
	s_nop 0
	v_cndmask_b32_e32 v162, v162, v163, vcc
	v_rsq_f32_e32 v162, v162
	s_nop 0
	v_mul_f32_e32 v163, 0x45800000, v162
	v_cndmask_b32_e32 v162, v162, v163, vcc
	v_pk_mul_f32 v[14:15], v[14:15], v[162:163] op_sel_hi:[1,0]
	v_pk_mul_f32 v[16:17], v[16:17], v[162:163] op_sel_hi:[1,0]
	v_pk_mul_f32 v[10:11], v[10:11], v[162:163] op_sel_hi:[1,0]
	v_pk_mul_f32 v[12:13], v[12:13], v[162:163] op_sel_hi:[1,0]
	v_pk_mul_f32 v[6:7], v[6:7], v[162:163] op_sel_hi:[1,0]
	v_pk_mul_f32 v[8:9], v[8:9], v[162:163] op_sel_hi:[1,0]
	v_pk_mul_f32 v[170:171], v[2:3], v[162:163] op_sel_hi:[1,0]
	v_pk_mul_f32 v[4:5], v[4:5], v[162:163] op_sel_hi:[1,0]
	v_cmp_lt_i32_e32 vcc, s63, v155
	s_waitcnt vmcnt(3)
	v_pk_mul_f32 v[168:169], v[160:161], v[16:17]
	v_pk_mul_f32 v[2:3], v[158:159], v[14:15]
	s_waitcnt vmcnt(2)
	v_pk_mul_f32 v[162:163], v[166:167], v[12:13]
	v_pk_mul_f32 v[160:161], v[164:165], v[10:11]
	s_waitcnt vmcnt(1)
	v_pk_mul_f32 v[166:167], v[184:185], v[8:9]
	v_pk_mul_f32 v[164:165], v[182:183], v[6:7]
	s_waitcnt vmcnt(0)
	v_pk_mul_f32 v[158:159], v[188:189], v[4:5]
	v_pk_mul_f32 v[4:5], v[186:187], v[170:171]
	s_and_saveexec_b64 s[38:39], vcc
	s_cbranch_execz .LBB0_148
	v_add_u32_e32 v6, 0xffffff00, v155
	v_lshlrev_b32_e32 v10, 6, v155
	v_and_b32_e32 v14, 0xffffffc0, v6
	v_mov_b32_e32 v15, v131
	v_and_b32_e32 v170, 0x3c0, v10
	v_mov_b32_e32 v171, v131
	v_lshl_add_u64 v[6:7], v[140:141], 0, v[14:15]
	v_lshl_add_u64 v[10:11], v[140:141], 0, v[170:171]
	global_load_dwordx4 v[6:9], v[6:7], off
	v_lshl_add_u64 v[14:15], v[138:139], 0, v[14:15]
	global_load_dwordx4 v[10:13], v[10:11], off
	v_lshl_add_u64 v[170:171], v[138:139], 0, v[170:171]
	global_load_dwordx4 v[14:17], v[14:15], off
	s_waitcnt vmcnt(2)
	v_pk_mul_f32 v[186:187], v[160:161], v[6:7]
	global_load_dwordx4 v[182:185], v[170:171], off
	v_pk_mul_f32 v[170:171], v[162:163], v[8:9]
	v_pk_mul_f32 v[8:9], v[168:169], v[8:9]
	v_pk_mul_f32 v[6:7], v[2:3], v[6:7]
	s_waitcnt vmcnt(2)
	v_pk_mul_f32 v[188:189], v[158:159], v[12:13]
	v_pk_mul_f32 v[190:191], v[4:5], v[10:11]
	v_pk_mul_f32 v[12:13], v[166:167], v[12:13]
	v_pk_mul_f32 v[10:11], v[164:165], v[10:11]
	s_waitcnt vmcnt(1)
	v_pk_fma_f32 v[168:169], v[168:169], v[16:17], v[170:171] neg_lo:[0,0,1] neg_hi:[0,0,1]
	v_pk_fma_f32 v[2:3], v[2:3], v[14:15], v[186:187] neg_lo:[0,0,1] neg_hi:[0,0,1]
	v_pk_fma_f32 v[162:163], v[162:163], v[16:17], v[8:9]
	v_pk_fma_f32 v[160:161], v[160:161], v[14:15], v[6:7]
	s_waitcnt vmcnt(0)
	v_pk_fma_f32 v[166:167], v[166:167], v[184:185], v[188:189] neg_lo:[0,0,1] neg_hi:[0,0,1]
	v_pk_fma_f32 v[164:165], v[164:165], v[182:183], v[190:191] neg_lo:[0,0,1] neg_hi:[0,0,1]
	v_pk_fma_f32 v[158:159], v[158:159], v[184:185], v[12:13]
	v_pk_fma_f32 v[4:5], v[4:5], v[182:183], v[10:11]
